# prompt attention loop back edge: loop-carried max copy moved ahead of the tile barrier, single conditional back-branch after it
# baseline (speedup 1.0000x reference)
;     ...
;         const float mnew = fmaxf(mrun, mx), alpha = __builtin_amdgcn_exp2f(mrun - mnew);
;         const bool resc = __builtin_amdgcn_ballot_w64(mnew != mrun) != 0ull; mrun = mnew;
;     ...
;         for (int t = 0; t < ntiles; ++t) { const int cur = t & 1;
;             if (t + 1 < ntiles) lstore(cur ^ 1);
;             if (t + 2 < ntiles) gload(t + 2);
;             if (t <= tmax_w) compute((const bf16_t*)(lds + cur * BUFB), (const bf16_t*)(lds + cur * BUFB + 64 * KSTR * 2), t);
;             __syncthreads();
;         }
.LBB0_1928:
	s_add_i32 s16, s16, 1
	s_add_i32 s46, s46, 64
	s_cmp_lg_u32 s15, s16
	v_mov_b32_e32 v224, v15
	s_waitcnt lgkmcnt(0)
	s_barrier
	s_cbranch_scc1 .LBB0_1907
